# qkv epilogue: rope-table loads of both 8-row halves of an epilogue iteration issued together (4 instead of 8 serial L2 round trips per tile)
# speedup vs baseline: 1.0072x; 1.0072x over previous
.LBB0_241:
	ds_read_b128 v[0:3], v29
	ds_read_b128 v[4:7], v29 offset:16
	s_and_saveexec_b64 s[72:73], s[64:65]
	s_xor_b64 s[72:73], exec, s[72:73]
	s_or_saveexec_b64 s[72:73], s[72:73]
	v_add_u32_e32 v24, s78, v28
	v_add_u32_e32 v30, v29, v13
	s_xor_b64 exec, exec, s[72:73]
	s_cbranch_execz .LBB0_243
	v_lshrrev_b32_e32 v8, 6, v24
	v_cndmask_b32_e64 v8, v24, v8, s[46:47]
	v_lshlrev_b32_e32 v8, 6, v8
	v_and_b32_e32 v128, 0xfc0, v8
	v_lshl_add_u64 v[26:27], v[22:23], 0, v[128:129]
	global_load_dwordx4 v[8:11], v[26:27], off
	global_load_dwordx4 v[32:35], v[26:27], off offset:16
	v_lshl_add_u64 v[26:27], v[14:15], 0, v[128:129]
	global_load_dwordx4 v[40:43], v[26:27], off
	global_load_dwordx4 v[44:47], v[26:27], off offset:16
	v_add_u32_e32 v158, 8, v24
	v_lshrrev_b32_e32 v159, 6, v158
	v_cndmask_b32_e64 v158, v158, v159, s[46:47]
	v_lshlrev_b32_e32 v158, 6, v158
	v_and_b32_e32 v158, 0xfc0, v158
	v_mov_b32_e32 v159, 0
	v_lshl_add_u64 v[160:161], v[22:23], 0, v[158:159]
	global_load_dwordx4 v[142:145], v[160:161], off
	global_load_dwordx4 v[146:149], v[160:161], off offset:16
	v_lshl_add_u64 v[160:161], v[14:15], 0, v[158:159]
	global_load_dwordx4 v[150:153], v[160:161], off
	global_load_dwordx4 v[154:157], v[160:161], off offset:16
	ds_read_b128 v[36:39], v30
	ds_read_b128 v[48:51], v30 offset:16
	s_waitcnt vmcnt(7) lgkmcnt(1)
	v_mul_f32_e32 v8, v36, v8
	v_mul_f32_e32 v9, v37, v9
	v_mul_f32_e32 v10, v38, v10
	v_mul_f32_e32 v11, v39, v11
	s_waitcnt vmcnt(6) lgkmcnt(0)
	v_mul_f32_e32 v25, v48, v32
	v_mul_f32_e32 v26, v49, v33
	v_mul_f32_e32 v27, v50, v34
	v_mul_f32_e32 v31, v51, v35
	v_cndmask_b32_e64 v32, v8, -v8, s[48:49]
	v_cndmask_b32_e64 v33, v9, -v9, s[48:49]
	v_cndmask_b32_e64 v34, v10, -v10, s[48:49]
	v_cndmask_b32_e64 v35, v11, -v11, s[48:49]
	v_cndmask_b32_e64 v36, v25, -v25, s[48:49]
	v_cndmask_b32_e64 v37, v26, -v26, s[48:49]
	v_cndmask_b32_e64 v38, v27, -v27, s[48:49]
	v_cndmask_b32_e64 v39, v31, -v31, s[48:49]
	s_waitcnt vmcnt(5)
	v_fmac_f32_e32 v32, v0, v40
	v_fmac_f32_e32 v33, v1, v41
	v_fmac_f32_e32 v34, v2, v42
	v_fmac_f32_e32 v35, v3, v43
	s_waitcnt vmcnt(4)
	v_fmac_f32_e32 v36, v4, v44
	v_fmac_f32_e32 v37, v5, v45
	v_fmac_f32_e32 v38, v6, v46
	v_fmac_f32_e32 v39, v7, v47
	v_mov_b64_e32 v[0:1], v[32:33]
	v_mov_b64_e32 v[2:3], v[34:35]
	v_mov_b64_e32 v[4:5], v[36:37]
	v_mov_b64_e32 v[6:7], v[38:39]

.LBB0_255:
	ds_read_b128 v[0:3], v29 offset:2176
	ds_read_b128 v[4:7], v29 offset:2192
	s_and_saveexec_b64 s[72:73], s[64:65]
	s_xor_b64 s[72:73], exec, s[72:73]
	s_or_saveexec_b64 s[72:73], s[72:73]
	v_add_u32_e32 v24, 8, v24
	s_xor_b64 exec, exec, s[72:73]
	s_cbranch_execz .LBB0_259
	ds_read_b128 v[46:49], v30 offset:2176
	ds_read_b128 v[50:53], v30 offset:2192
	s_waitcnt vmcnt(4) lgkmcnt(1)
	v_mul_f32_e32 v8, v46, v142
	v_mul_f32_e32 v9, v47, v143
	v_mul_f32_e32 v10, v48, v144
	v_mul_f32_e32 v11, v49, v145
	s_waitcnt vmcnt(3) lgkmcnt(0)
	v_mul_f32_e32 v25, v50, v146
	v_mul_f32_e32 v26, v51, v147
	v_mul_f32_e32 v27, v52, v148
	v_mul_f32_e32 v37, v53, v149
	v_cndmask_b32_e64 v30, v8, -v8, s[48:49]
	v_cndmask_b32_e64 v31, v9, -v9, s[48:49]
	v_cndmask_b32_e64 v32, v10, -v10, s[48:49]
	v_cndmask_b32_e64 v33, v11, -v11, s[48:49]
	v_cndmask_b32_e64 v34, v25, -v25, s[48:49]
	v_cndmask_b32_e64 v35, v26, -v26, s[48:49]
	v_cndmask_b32_e64 v36, v27, -v27, s[48:49]
	v_cndmask_b32_e64 v37, v37, -v37, s[48:49]
	s_waitcnt vmcnt(2)
	v_fmac_f32_e32 v30, v0, v150
	v_fmac_f32_e32 v31, v1, v151
	v_fmac_f32_e32 v32, v2, v152
	v_fmac_f32_e32 v33, v3, v153
	s_waitcnt vmcnt(1)
	v_fmac_f32_e32 v34, v4, v154
	v_fmac_f32_e32 v35, v5, v155
	v_fmac_f32_e32 v36, v6, v156
	v_fmac_f32_e32 v37, v7, v157
	v_mov_b64_e32 v[0:1], v[30:31]
	v_mov_b64_e32 v[2:3], v[32:33]
	v_mov_b64_e32 v[4:5], v[34:35]
	v_mov_b64_e32 v[6:7], v[36:37]
